# in-proj and FF1 K-loops: LDS-DMA M0 destinations formed by s_add_u32 from one per-step scalar base instead of v_add/v_readfirstlane/s_mov per load (17 fewer VALU per K-step)
# baseline (speedup 1.0000x reference)
gp151_skip:
	v_readfirstlane_b32 s99, v74
.LBB0_151:
	s_and_b32 s8, s7, 0x8000
	s_xor_b32 s9, s8, 0x8000
	s_add_u32 s98, s9, s99
	v_lshl_add_u64 v[80:81], v[64:65], 0, s[4:5]
	v_lshl_add_u64 v[82:83], v[80:81], 0, s[28:29]
	s_add_u32 m0, s98, 0x0
	v_lshl_add_u64 v[84:85], v[66:67], 0, s[4:5]
	global_load_lds_dwordx4 v[82:83], off
	v_lshl_add_u64 v[86:87], v[84:85], 0, s[28:29]
	s_add_u32 m0, s98, 0x4000
	v_lshl_add_u64 v[82:83], v[80:81], 0, s[10:11]
	global_load_lds_dwordx4 v[86:87], off
	s_add_u32 m0, s98, 0x1000
	s_nop 0
	global_load_lds_dwordx4 v[82:83], off
	v_lshl_add_u64 v[82:83], v[84:85], 0, s[10:11]
	s_add_u32 m0, s98, 0x5000
	s_nop 0
	global_load_lds_dwordx4 v[82:83], off
	v_lshl_add_u64 v[82:83], v[80:81], 0, s[14:15]
	s_add_u32 m0, s98, 0x2000
	s_nop 0
	global_load_lds_dwordx4 v[82:83], off
	v_lshl_add_u64 v[82:83], v[84:85], 0, s[14:15]
	s_add_u32 m0, s98, 0x6000
	v_lshl_add_u64 v[80:81], v[80:81], 0, s[12:13]
	global_load_lds_dwordx4 v[82:83], off
	s_add_u32 m0, s98, 0x3000
	s_nop 0
	global_load_lds_dwordx4 v[80:81], off
	v_lshl_add_u64 v[80:81], v[84:85], 0, s[12:13]
	s_add_u32 m0, s98, 0x7000
	v_or_b32_e32 v79, s8, v76
	global_load_lds_dwordx4 v[80:81], off
	v_add_u32_e32 v100, v79, v75
	v_add_u32_e32 v79, v79, v77
	ds_read_b128 v[80:83], v100
	ds_read_b128 v[84:87], v100 offset:2048
	ds_read_b128 v[88:91], v79 offset:16384
	ds_read_b128 v[92:95], v79 offset:18432
	ds_read_b128 v[96:99], v100 offset:4096
	ds_read_b128 v[100:103], v100 offset:6144
	ds_read_b128 v[104:107], v79 offset:20480
	ds_read_b128 v[108:111], v79 offset:22528
	v_or_b32_e32 v79, s8, v78
	v_add_u32_e32 v132, v79, v75
	v_add_u32_e32 v79, v79, v77
	ds_read_b128 v[112:115], v132
	ds_read_b128 v[116:119], v132 offset:2048
	ds_read_b128 v[120:123], v79 offset:16384
	ds_read_b128 v[124:127], v79 offset:18432
	ds_read_b128 v[128:131], v132 offset:4096
	ds_read_b128 v[132:135], v132 offset:6144
	ds_read_b128 v[146:149], v79 offset:20480
	ds_read_b128 v[150:153], v79 offset:22528
	s_waitcnt lgkmcnt(0)
	v_mfma_f32_16x16x32_bf16 v[60:63], v[80:83], v[88:91], v[60:63]
	v_mfma_f32_16x16x32_bf16 v[56:59], v[80:83], v[92:95], v[56:59]
	v_mfma_f32_16x16x32_bf16 v[52:55], v[80:83], v[104:107], v[52:55]
	v_mfma_f32_16x16x32_bf16 v[48:51], v[80:83], v[108:111], v[48:51]
	v_mfma_f32_16x16x32_bf16 v[44:47], v[84:87], v[88:91], v[44:47]
	v_mfma_f32_16x16x32_bf16 v[40:43], v[84:87], v[92:95], v[40:43]
	v_mfma_f32_16x16x32_bf16 v[36:39], v[84:87], v[104:107], v[36:39]
	v_mfma_f32_16x16x32_bf16 v[32:35], v[84:87], v[108:111], v[32:35]
	v_mfma_f32_16x16x32_bf16 v[28:31], v[96:99], v[88:91], v[28:31]
	v_mfma_f32_16x16x32_bf16 v[24:27], v[96:99], v[92:95], v[24:27]
	v_mfma_f32_16x16x32_bf16 v[20:23], v[96:99], v[104:107], v[20:23]
	v_mfma_f32_16x16x32_bf16 v[16:19], v[96:99], v[108:111], v[16:19]
	v_mfma_f32_16x16x32_bf16 v[12:15], v[100:103], v[88:91], v[12:15]
	v_mfma_f32_16x16x32_bf16 v[8:11], v[100:103], v[92:95], v[8:11]
	v_mfma_f32_16x16x32_bf16 v[4:7], v[100:103], v[104:107], v[4:7]
	v_mfma_f32_16x16x32_bf16 v[0:3], v[100:103], v[108:111], v[0:3]
	v_mfma_f32_16x16x32_bf16 v[60:63], v[112:115], v[120:123], v[60:63]
	v_mfma_f32_16x16x32_bf16 v[56:59], v[112:115], v[124:127], v[56:59]
	v_mfma_f32_16x16x32_bf16 v[52:55], v[112:115], v[146:149], v[52:55]
	v_mfma_f32_16x16x32_bf16 v[48:51], v[112:115], v[150:153], v[48:51]
	v_mfma_f32_16x16x32_bf16 v[44:47], v[116:119], v[120:123], v[44:47]
	v_mfma_f32_16x16x32_bf16 v[40:43], v[116:119], v[124:127], v[40:43]
	v_mfma_f32_16x16x32_bf16 v[36:39], v[116:119], v[146:149], v[36:39]
	v_mfma_f32_16x16x32_bf16 v[32:35], v[116:119], v[150:153], v[32:35]
	v_mfma_f32_16x16x32_bf16 v[28:31], v[128:131], v[120:123], v[28:31]
	v_mfma_f32_16x16x32_bf16 v[24:27], v[128:131], v[124:127], v[24:27]
	v_mfma_f32_16x16x32_bf16 v[20:23], v[128:131], v[146:149], v[20:23]
	v_mfma_f32_16x16x32_bf16 v[16:19], v[128:131], v[150:153], v[16:19]
	v_mfma_f32_16x16x32_bf16 v[12:15], v[132:135], v[120:123], v[12:15]
	v_mfma_f32_16x16x32_bf16 v[8:11], v[132:135], v[124:127], v[8:11]
	v_mfma_f32_16x16x32_bf16 v[4:7], v[132:135], v[146:149], v[4:7]
	v_mfma_f32_16x16x32_bf16 v[0:3], v[132:135], v[150:153], v[0:3]
	s_add_i32 s7, s7, 0x8000
	s_waitcnt vmcnt(0)
	s_add_u32 s4, s4, 0x80
	s_addc_u32 s5, s5, 0
	s_cmpk_lg_i32 s4, 0x780
	s_barrier
	s_cbranch_scc1 .LBB0_151
	s_setprio 0
	v_add_u32_e32 v74, v78, v77
	v_add_u32_e32 v102, v78, v75
	v_add_u32_e32 v122, v76, v77
	v_add_u32_e32 v130, v76, v75
	ds_read_b128 v[64:67], v74 offset:55296
	ds_read_b128 v[78:81], v74 offset:53248
	ds_read_b128 v[82:85], v102 offset:38912
	ds_read_b128 v[86:89], v102 offset:36864
	ds_read_b128 v[90:93], v74 offset:51200
	ds_read_b128 v[94:97], v74 offset:49152
	ds_read_b128 v[98:101], v102 offset:34816
	ds_read_b128 v[102:105], v102 offset:32768
	ds_read_b128 v[74:77], v122 offset:55296
	ds_read_b128 v[106:109], v122 offset:53248
	ds_read_b128 v[110:113], v130 offset:38912
	ds_read_b128 v[114:117], v130 offset:36864
	ds_read_b128 v[118:121], v122 offset:51200
	ds_read_b128 v[122:125], v122 offset:49152
	ds_read_b128 v[126:129], v130 offset:34816
	ds_read_b128 v[130:133], v130 offset:32768
	v_and_b32_e32 v134, 64, v69
	s_waitcnt lgkmcnt(0)
	v_mfma_f32_16x16x32_bf16 v[60:63], v[130:133], v[122:125], v[60:63]
	v_mfma_f32_16x16x32_bf16 v[56:59], v[130:133], v[118:121], v[56:59]
	v_mfma_f32_16x16x32_bf16 v[52:55], v[130:133], v[106:109], v[52:55]
	v_mfma_f32_16x16x32_bf16 v[48:51], v[130:133], v[74:77], v[48:51]
	v_mfma_f32_16x16x32_bf16 v[44:47], v[126:129], v[122:125], v[44:47]
	v_mfma_f32_16x16x32_bf16 v[40:43], v[126:129], v[118:121], v[40:43]
	v_mfma_f32_16x16x32_bf16 v[36:39], v[126:129], v[106:109], v[36:39]
	v_mfma_f32_16x16x32_bf16 v[32:35], v[126:129], v[74:77], v[32:35]
	v_mfma_f32_16x16x32_bf16 v[28:31], v[114:117], v[122:125], v[28:31]
	v_mfma_f32_16x16x32_bf16 v[24:27], v[114:117], v[118:121], v[24:27]
	v_mfma_f32_16x16x32_bf16 v[20:23], v[114:117], v[106:109], v[20:23]
	v_mfma_f32_16x16x32_bf16 v[16:19], v[114:117], v[74:77], v[16:19]
	v_mfma_f32_16x16x32_bf16 v[12:15], v[110:113], v[122:125], v[12:15]
	v_mfma_f32_16x16x32_bf16 v[8:11], v[110:113], v[118:121], v[8:11]
	v_mfma_f32_16x16x32_bf16 v[4:7], v[110:113], v[106:109], v[4:7]
	v_mfma_f32_16x16x32_bf16 v[0:3], v[110:113], v[74:77], v[0:3]
	v_mfma_f32_16x16x32_bf16 v[60:63], v[102:105], v[94:97], v[60:63]
	v_mfma_f32_16x16x32_bf16 v[56:59], v[102:105], v[90:93], v[56:59]
	v_mfma_f32_16x16x32_bf16 v[52:55], v[102:105], v[78:81], v[52:55]
	v_mfma_f32_16x16x32_bf16 v[48:51], v[102:105], v[64:67], v[48:51]
	v_mfma_f32_16x16x32_bf16 v[44:47], v[98:101], v[94:97], v[44:47]
	v_mfma_f32_16x16x32_bf16 v[40:43], v[98:101], v[90:93], v[40:43]
	v_mfma_f32_16x16x32_bf16 v[36:39], v[98:101], v[78:81], v[36:39]
	v_mfma_f32_16x16x32_bf16 v[32:35], v[98:101], v[64:67], v[32:35]
	v_mfma_f32_16x16x32_bf16 v[28:31], v[86:89], v[94:97], v[28:31]
	v_mfma_f32_16x16x32_bf16 v[24:27], v[86:89], v[90:93], v[24:27]
	v_mfma_f32_16x16x32_bf16 v[20:23], v[86:89], v[78:81], v[20:23]
	v_mfma_f32_16x16x32_bf16 v[16:19], v[86:89], v[64:67], v[16:19]
	v_mfma_f32_16x16x32_bf16 v[12:15], v[82:85], v[94:97], v[12:15]
	v_mfma_f32_16x16x32_bf16 v[8:11], v[82:85], v[90:93], v[8:11]
	v_mfma_f32_16x16x32_bf16 v[4:7], v[82:85], v[78:81], v[4:7]
	v_mfma_f32_16x16x32_bf16 v[0:3], v[82:85], v[64:67], v[0:3]
	s_movk_i32 s4, 0x2400
	v_max_f32_e32 v60, v60, v60
	v_max_f32_e32 v56, v56, v56
	v_max_f32_e32 v52, v52, v52
	v_max_f32_e32 v48, v48, v48
	v_max_f32_e32 v44, v44, v44
	v_max_f32_e32 v40, v40, v40
	v_max_f32_e32 v36, v36, v36
	v_max_f32_e32 v32, v32, v32
	v_max_f32_e32 v28, v28, v28
	v_max_f32_e32 v24, v24, v24
	v_max_f32_e32 v20, v20, v20
	v_max_f32_e32 v16, v16, v16
	v_max_f32_e32 v12, v12, v12
	v_max_f32_e32 v8, v8, v8
	v_max_f32_e32 v4, v4, v4
	v_max_f32_e32 v0, v0, v0
	v_mul_lo_u32 v64, v72, s4
	v_max_f32_e32 v60, 0, v60
	v_max_f32_e32 v61, v61, v61
	v_max_f32_e32 v56, 0, v56
	v_max_f32_e32 v57, v57, v57
	v_max_f32_e32 v52, 0, v52
	v_max_f32_e32 v53, v53, v53
	v_max_f32_e32 v48, 0, v48
	v_max_f32_e32 v49, v49, v49
	v_max_f32_e32 v44, 0, v44
	v_max_f32_e32 v45, v45, v45
	v_max_f32_e32 v40, 0, v40
	v_max_f32_e32 v41, v41, v41
	v_max_f32_e32 v36, 0, v36
	v_max_f32_e32 v37, v37, v37
	v_max_f32_e32 v32, 0, v32
	v_max_f32_e32 v33, v33, v33
	v_max_f32_e32 v28, 0, v28
	v_max_f32_e32 v29, v29, v29
	v_max_f32_e32 v24, 0, v24
	v_max_f32_e32 v25, v25, v25
	v_max_f32_e32 v20, 0, v20
	v_max_f32_e32 v21, v21, v21
	v_max_f32_e32 v16, 0, v16
	v_max_f32_e32 v17, v17, v17
	v_max_f32_e32 v12, 0, v12
	v_max_f32_e32 v13, v13, v13
	v_max_f32_e32 v8, 0, v8
	v_max_f32_e32 v9, v9, v9
	v_max_f32_e32 v4, 0, v4
	v_max_f32_e32 v5, v5, v5
	v_max_f32_e32 v0, 0, v0
	v_max_f32_e32 v1, v1, v1
	v_lshl_or_b32 v65, v73, 1, v64
	v_mul_f32_e32 v60, v60, v60
	v_max_f32_e32 v61, 0, v61
	v_max_f32_e32 v62, v62, v62
	s_movk_i32 s4, 0x240
	v_mul_f32_e32 v56, v56, v56
	v_max_f32_e32 v57, 0, v57
	v_max_f32_e32 v58, v58, v58
	v_mul_f32_e32 v52, v52, v52
	v_max_f32_e32 v53, 0, v53
	v_max_f32_e32 v54, v54, v54
	v_mul_f32_e32 v48, v48, v48
	v_max_f32_e32 v49, 0, v49
	v_max_f32_e32 v50, v50, v50
	v_mul_f32_e32 v44, v44, v44
	v_max_f32_e32 v45, 0, v45
	v_max_f32_e32 v46, v46, v46
	v_mul_f32_e32 v40, v40, v40
	v_max_f32_e32 v41, 0, v41
	v_max_f32_e32 v42, v42, v42
	v_mul_f32_e32 v36, v36, v36
	v_max_f32_e32 v37, 0, v37
	v_max_f32_e32 v38, v38, v38
	v_mul_f32_e32 v32, v32, v32
	v_max_f32_e32 v33, 0, v33
	v_max_f32_e32 v34, v34, v34
	v_mul_f32_e32 v28, v28, v28
	v_max_f32_e32 v29, 0, v29
	v_max_f32_e32 v30, v30, v30
	v_mul_f32_e32 v24, v24, v24
	v_max_f32_e32 v25, 0, v25
	v_max_f32_e32 v26, v26, v26
	v_mul_f32_e32 v20, v20, v20
	v_max_f32_e32 v21, 0, v21
	v_max_f32_e32 v22, v22, v22
	v_mul_f32_e32 v16, v16, v16
	v_max_f32_e32 v17, 0, v17
	v_max_f32_e32 v18, v18, v18
	v_mul_f32_e32 v12, v12, v12
	v_max_f32_e32 v13, 0, v13
	v_max_f32_e32 v14, v14, v14
	v_mul_f32_e32 v8, v8, v8
	v_max_f32_e32 v9, 0, v9
	v_max_f32_e32 v10, v10, v10
	v_mul_f32_e32 v4, v4, v4
	v_max_f32_e32 v5, 0, v5
	v_max_f32_e32 v6, v6, v6
	v_mul_f32_e32 v0, v0, v0
	v_max_f32_e32 v1, 0, v1
	v_max_f32_e32 v2, v2, v2
	v_mul_f32_e32 v61, v61, v61
	v_max_f32_e32 v62, 0, v62
	v_max_f32_e32 v63, v63, v63
	v_cvt_pk_bf16_f32 v60, v60, s0
	v_mad_u32_u24 v65, v71, s4, v65
	v_mul_f32_e32 v57, v57, v57
	v_max_f32_e32 v58, 0, v58
	v_max_f32_e32 v59, v59, v59
	v_cvt_pk_bf16_f32 v56, v56, s0
	v_mul_f32_e32 v53, v53, v53
	v_max_f32_e32 v54, 0, v54
	v_max_f32_e32 v55, v55, v55
	v_cvt_pk_bf16_f32 v52, v52, s0
	v_mul_f32_e32 v49, v49, v49
	v_max_f32_e32 v50, 0, v50
	v_max_f32_e32 v51, v51, v51
	v_cvt_pk_bf16_f32 v48, v48, s0
	v_mul_f32_e32 v45, v45, v45
	v_max_f32_e32 v46, 0, v46
	v_max_f32_e32 v47, v47, v47
	v_cvt_pk_bf16_f32 v44, v44, s0
	v_mul_f32_e32 v41, v41, v41
	v_max_f32_e32 v42, 0, v42
	v_max_f32_e32 v43, v43, v43
	v_cvt_pk_bf16_f32 v40, v40, s0
	v_mul_f32_e32 v37, v37, v37
	v_max_f32_e32 v38, 0, v38
	v_max_f32_e32 v39, v39, v39
	v_cvt_pk_bf16_f32 v36, v36, s0
	v_mul_f32_e32 v33, v33, v33
	v_max_f32_e32 v34, 0, v34
	v_max_f32_e32 v35, v35, v35
	v_cvt_pk_bf16_f32 v32, v32, s0
	v_mul_f32_e32 v29, v29, v29
	v_max_f32_e32 v30, 0, v30
	v_max_f32_e32 v31, v31, v31
	v_cvt_pk_bf16_f32 v28, v28, s0
	v_mul_f32_e32 v25, v25, v25
	v_max_f32_e32 v26, 0, v26
	v_max_f32_e32 v27, v27, v27
	v_cvt_pk_bf16_f32 v24, v24, s0
	v_mul_f32_e32 v21, v21, v21
	v_max_f32_e32 v22, 0, v22
	v_max_f32_e32 v23, v23, v23
	v_cvt_pk_bf16_f32 v20, v20, s0
	v_mul_f32_e32 v17, v17, v17
	v_max_f32_e32 v18, 0, v18
	v_max_f32_e32 v19, v19, v19
	v_cvt_pk_bf16_f32 v16, v16, s0
	v_mul_f32_e32 v13, v13, v13
	v_max_f32_e32 v14, 0, v14
	v_max_f32_e32 v15, v15, v15
	v_cvt_pk_bf16_f32 v12, v12, s0
	v_mul_f32_e32 v9, v9, v9
	v_max_f32_e32 v10, 0, v10
	v_max_f32_e32 v11, v11, v11
	v_cvt_pk_bf16_f32 v8, v8, s0
	v_mul_f32_e32 v5, v5, v5
	v_max_f32_e32 v6, 0, v6
	v_max_f32_e32 v7, v7, v7
	v_cvt_pk_bf16_f32 v4, v4, s0
	v_mul_f32_e32 v1, v1, v1
	v_max_f32_e32 v2, 0, v2
	v_max_f32_e32 v3, v3, v3
	v_cvt_pk_bf16_f32 v0, v0, s0
	s_waitcnt vmcnt(0)
	s_barrier
	v_mul_f32_e32 v62, v62, v62
	v_max_f32_e32 v63, 0, v63
	ds_write_b16 v65, v60
	v_cvt_pk_bf16_f32 v60, v61, s0
	v_mul_f32_e32 v58, v58, v58
	v_max_f32_e32 v59, 0, v59
	ds_write_b16 v65, v56 offset:32
	v_cvt_pk_bf16_f32 v56, v57, s0
	v_mul_f32_e32 v54, v54, v54
	v_max_f32_e32 v55, 0, v55
	ds_write_b16 v65, v52 offset:64
	v_cvt_pk_bf16_f32 v52, v53, s0
	v_mul_f32_e32 v50, v50, v50
	v_max_f32_e32 v51, 0, v51
	ds_write_b16 v65, v48 offset:96
	v_cvt_pk_bf16_f32 v48, v49, s0
	v_mul_f32_e32 v46, v46, v46
	v_max_f32_e32 v47, 0, v47
	ds_write_b16 v65, v44 offset:2304
	v_cvt_pk_bf16_f32 v44, v45, s0
	v_mul_f32_e32 v42, v42, v42
	v_max_f32_e32 v43, 0, v43
	ds_write_b16 v65, v40 offset:2336
	v_cvt_pk_bf16_f32 v40, v41, s0
	v_mul_f32_e32 v38, v38, v38
	v_max_f32_e32 v39, 0, v39
	ds_write_b16 v65, v36 offset:2368
	v_cvt_pk_bf16_f32 v36, v37, s0
	v_mul_f32_e32 v34, v34, v34
	v_max_f32_e32 v35, 0, v35
	ds_write_b16 v65, v32 offset:2400
	v_cvt_pk_bf16_f32 v32, v33, s0
	v_mul_f32_e32 v30, v30, v30
	v_max_f32_e32 v31, 0, v31
	ds_write_b16 v65, v28 offset:4608
	v_cvt_pk_bf16_f32 v28, v29, s0
	v_mul_f32_e32 v26, v26, v26
	v_max_f32_e32 v27, 0, v27
	ds_write_b16 v65, v24 offset:4640
	v_cvt_pk_bf16_f32 v24, v25, s0
	v_mul_f32_e32 v22, v22, v22
	v_max_f32_e32 v23, 0, v23
	ds_write_b16 v65, v20 offset:4672
	v_cvt_pk_bf16_f32 v20, v21, s0
	v_mul_f32_e32 v18, v18, v18
	v_max_f32_e32 v19, 0, v19
	ds_write_b16 v65, v16 offset:4704
	v_cvt_pk_bf16_f32 v16, v17, s0
	v_mul_f32_e32 v14, v14, v14
	v_max_f32_e32 v15, 0, v15
	ds_write_b16 v65, v12 offset:6912
	v_cvt_pk_bf16_f32 v12, v13, s0
	v_mul_f32_e32 v10, v10, v10
	v_max_f32_e32 v11, 0, v11
	ds_write_b16 v65, v8 offset:6944
	v_cvt_pk_bf16_f32 v8, v9, s0
	v_mul_f32_e32 v6, v6, v6
	v_max_f32_e32 v7, 0, v7
	ds_write_b16 v65, v4 offset:6976
	v_cvt_pk_bf16_f32 v4, v5, s0
	v_mul_f32_e32 v2, v2, v2
	v_max_f32_e32 v3, 0, v3
	ds_write_b16 v65, v0 offset:7008
	v_cvt_pk_bf16_f32 v0, v1, s0
	v_mul_f32_e32 v63, v63, v63
	ds_write_b16 v65, v60 offset:144
	v_cvt_pk_bf16_f32 v60, v62, s0
	v_mul_f32_e32 v59, v59, v59
	ds_write_b16 v65, v56 offset:176
	v_cvt_pk_bf16_f32 v56, v58, s0
	v_mul_f32_e32 v55, v55, v55
	ds_write_b16 v65, v52 offset:208
	v_cvt_pk_bf16_f32 v52, v54, s0
	v_mul_f32_e32 v51, v51, v51
	ds_write_b16 v65, v48 offset:240
	v_cvt_pk_bf16_f32 v48, v50, s0
	v_mul_f32_e32 v47, v47, v47
	ds_write_b16 v65, v44 offset:2448
	v_cvt_pk_bf16_f32 v44, v46, s0
	v_mul_f32_e32 v43, v43, v43
	ds_write_b16 v65, v40 offset:2480
	v_cvt_pk_bf16_f32 v40, v42, s0
	v_mul_f32_e32 v39, v39, v39
	ds_write_b16 v65, v36 offset:2512
	v_cvt_pk_bf16_f32 v36, v38, s0
	v_mul_f32_e32 v35, v35, v35
	ds_write_b16 v65, v32 offset:2544
	v_cvt_pk_bf16_f32 v32, v34, s0
	v_mul_f32_e32 v31, v31, v31
	ds_write_b16 v65, v28 offset:4752
	v_cvt_pk_bf16_f32 v28, v30, s0
	v_mul_f32_e32 v27, v27, v27
	ds_write_b16 v65, v24 offset:4784
	v_cvt_pk_bf16_f32 v24, v26, s0
	v_mul_f32_e32 v23, v23, v23
	ds_write_b16 v65, v20 offset:4816
	v_cvt_pk_bf16_f32 v20, v22, s0
	v_mul_f32_e32 v19, v19, v19
	ds_write_b16 v65, v16 offset:4848
	v_cvt_pk_bf16_f32 v16, v18, s0
	v_mul_f32_e32 v15, v15, v15
	ds_write_b16 v65, v12 offset:7056
	v_cvt_pk_bf16_f32 v12, v14, s0
	v_mul_f32_e32 v11, v11, v11
	ds_write_b16 v65, v8 offset:7088
	v_cvt_pk_bf16_f32 v8, v10, s0
	v_mul_f32_e32 v7, v7, v7
	ds_write_b16 v65, v4 offset:7120
	v_cvt_pk_bf16_f32 v4, v6, s0
	v_mul_f32_e32 v3, v3, v3
	ds_write_b16 v65, v0 offset:7152
	v_cvt_pk_bf16_f32 v0, v2, s0
	v_add_u32_e32 v5, s1, v70
	s_ashr_i32 s1, s0, 31
	v_readlane_b32 s36, v246, 25
	ds_write_b16 v65, v60 offset:288
	v_cvt_pk_bf16_f32 v60, v63, s0
	ds_write_b16 v65, v56 offset:320
	v_cvt_pk_bf16_f32 v56, v59, s0
	ds_write_b16 v65, v52 offset:352
	v_cvt_pk_bf16_f32 v52, v55, s0
	ds_write_b16 v65, v48 offset:384
	v_cvt_pk_bf16_f32 v48, v51, s0
	ds_write_b16 v65, v44 offset:2592
	v_cvt_pk_bf16_f32 v44, v47, s0
	ds_write_b16 v65, v40 offset:2624
	v_cvt_pk_bf16_f32 v40, v43, s0
	ds_write_b16 v65, v36 offset:2656
	v_cvt_pk_bf16_f32 v36, v39, s0
	ds_write_b16 v65, v32 offset:2688
	v_cvt_pk_bf16_f32 v32, v35, s0
	ds_write_b16 v65, v28 offset:4896
	v_cvt_pk_bf16_f32 v28, v31, s0
	ds_write_b16 v65, v24 offset:4928
	v_cvt_pk_bf16_f32 v24, v27, s0
	ds_write_b16 v65, v20 offset:4960
	v_cvt_pk_bf16_f32 v20, v23, s0
	ds_write_b16 v65, v16 offset:4992
	v_cvt_pk_bf16_f32 v16, v19, s0
	ds_write_b16 v65, v12 offset:7200
	v_cvt_pk_bf16_f32 v12, v15, s0
	ds_write_b16 v65, v8 offset:7232
	v_cvt_pk_bf16_f32 v8, v11, s0
	ds_write_b16 v65, v4 offset:7264
	v_cvt_pk_bf16_f32 v4, v7, s0
	ds_write_b16 v65, v0 offset:7296
	v_cvt_pk_bf16_f32 v0, v3, s0
	s_lshl_b64 s[0:1], s[0:1], 1
	v_readlane_b32 s38, v246, 27
	ds_write_b16 v65, v0 offset:7440
	v_lshlrev_b32_e32 v0, 4, v69
	v_readlane_b32 s39, v246, 28
	s_add_u32 s0, s38, s0
	v_and_b32_e32 v0, 0x70, v0
	s_addc_u32 s1, s39, s1
	v_lshlrev_b32_e32 v136, 1, v134
	ds_write_b16 v65, v4 offset:7408
	v_or_b32_e32 v4, v64, v0
	v_lshl_add_u64 v[2:3], s[0:1], 0, v[136:137]
	s_movk_i32 s0, 0x90
	ds_write_b16 v65, v60 offset:432
	ds_write_b16 v65, v56 offset:464
	ds_write_b16 v65, v52 offset:496
	ds_write_b16 v65, v48 offset:528
	ds_write_b16 v65, v44 offset:2736
	ds_write_b16 v65, v40 offset:2768
	ds_write_b16 v65, v36 offset:2800
	ds_write_b16 v65, v32 offset:2832
	ds_write_b16 v65, v28 offset:5040
	ds_write_b16 v65, v24 offset:5072
	ds_write_b16 v65, v20 offset:5104
	ds_write_b16 v65, v16 offset:5136
	ds_write_b16 v65, v12 offset:7344
	ds_write_b16 v65, v8 offset:7376
	v_mov_b32_e32 v1, v137
	v_mad_u32_u24 v12, v68, s0, v4
	v_lshl_add_u64 v[8:9], v[2:3], 0, v[0:1]
	ds_read_b128 v[0:3], v12
	v_or_b32_e32 v13, v5, v68
	ds_read_b128 v[4:7], v12 offset:1152
	s_movk_i32 s4, 0x2080
	v_mad_i64_i32 v[10:11], s[0:1], v13, s4, v[8:9]
	s_waitcnt lgkmcnt(1)
	global_store_dwordx4 v[10:11], v[0:3], off
	s_add_i32 s6, s6, 1
	s_movk_i32 s36, 0x880
	v_or_b32_e32 v0, 8, v13
	v_mad_i64_i32 v[0:1], s[0:1], v0, s4, v[8:9]
	s_waitcnt lgkmcnt(0)
	global_store_dwordx4 v[0:1], v[4:7], off
	ds_read_b128 v[0:3], v12 offset:2304
	v_readlane_b32 s37, v246, 26
	v_or_b32_e32 v4, 16, v13
	v_mad_i64_i32 v[10:11], s[0:1], v4, s4, v[8:9]
	ds_read_b128 v[4:7], v12 offset:3456
	s_waitcnt lgkmcnt(1)
	global_store_dwordx4 v[10:11], v[0:3], off
	v_readlane_b32 s40, v246, 29
	v_readlane_b32 s41, v246, 30
	v_or_b32_e32 v0, 24, v13
	v_mad_i64_i32 v[0:1], s[0:1], v0, s4, v[8:9]
	s_waitcnt lgkmcnt(0)
	global_store_dwordx4 v[0:1], v[4:7], off
	ds_read_b128 v[0:3], v12 offset:4608
	v_readlane_b32 s42, v246, 31
	v_or_b32_e32 v4, 32, v13
	v_mad_i64_i32 v[10:11], s[0:1], v4, s4, v[8:9]
	ds_read_b128 v[4:7], v12 offset:5760
	s_waitcnt lgkmcnt(1)
	global_store_dwordx4 v[10:11], v[0:3], off
	v_readlane_b32 s43, v246, 32
	v_readlane_b32 s44, v246, 33
	v_or_b32_e32 v0, 40, v13
	v_mad_i64_i32 v[0:1], s[0:1], v0, s4, v[8:9]
	s_waitcnt lgkmcnt(0)
	global_store_dwordx4 v[0:1], v[4:7], off
	ds_read_b128 v[0:3], v12 offset:6912
	v_readlane_b32 s45, v246, 34
	v_or_b32_e32 v4, 48, v13
	v_mad_i64_i32 v[10:11], s[0:1], v4, s4, v[8:9]
	ds_read_b128 v[4:7], v12 offset:8064
	s_waitcnt lgkmcnt(1)
	global_store_dwordx4 v[10:11], v[0:3], off
	v_readlane_b32 s46, v246, 35
	v_readlane_b32 s47, v246, 36
	v_or_b32_e32 v0, 56, v13
	v_mad_i64_i32 v[0:1], s[0:1], v0, s4, v[8:9]
	s_mov_b64 s[4:5], 0
	v_readlane_b32 s48, v246, 37
	v_readlane_b32 s49, v246, 38
	v_readlane_b32 s50, v246, 39
	v_readlane_b32 s51, v246, 40
	s_waitcnt lgkmcnt(0)
	global_store_dwordx4 v[0:1], v[4:7], off
	s_barrier
	s_branch .LBB0_141

gp1106_skip:
	v_readfirstlane_b32 s99, v74
.LBB0_1106:
	s_and_b32 s10, s9, 0x8000
	s_xor_b32 s11, s10, 0x8000
	s_add_u32 s98, s11, s99
	v_lshl_add_u64 v[80:81], v[64:65], 0, s[4:5]
	v_lshl_add_u64 v[82:83], v[80:81], 0, s[28:29]
	s_add_u32 m0, s98, 0x0
	v_lshl_add_u64 v[84:85], v[66:67], 0, s[4:5]
	global_load_lds_dwordx4 v[82:83], off
	v_lshl_add_u64 v[86:87], v[84:85], 0, s[28:29]
	s_add_u32 m0, s98, 0x4000
	v_lshl_add_u64 v[82:83], v[80:81], 0, s[12:13]
	global_load_lds_dwordx4 v[86:87], off
	s_add_u32 m0, s98, 0x1000
	s_nop 0
	global_load_lds_dwordx4 v[82:83], off
	v_lshl_add_u64 v[82:83], v[84:85], 0, s[12:13]
	s_add_u32 m0, s98, 0x5000
	s_nop 0
	global_load_lds_dwordx4 v[82:83], off
	v_lshl_add_u64 v[82:83], v[80:81], 0, s[16:17]
	s_add_u32 m0, s98, 0x2000
	s_nop 0
	global_load_lds_dwordx4 v[82:83], off
	v_lshl_add_u64 v[82:83], v[84:85], 0, s[16:17]
	s_add_u32 m0, s98, 0x6000
	v_lshl_add_u64 v[80:81], v[80:81], 0, s[14:15]
	global_load_lds_dwordx4 v[82:83], off
	s_add_u32 m0, s98, 0x3000
	s_nop 0
	global_load_lds_dwordx4 v[80:81], off
	v_lshl_add_u64 v[80:81], v[84:85], 0, s[14:15]
	s_add_u32 m0, s98, 0x7000
	v_or_b32_e32 v79, s10, v76
	global_load_lds_dwordx4 v[80:81], off
	v_add_u32_e32 v100, v79, v75
	v_add_u32_e32 v79, v79, v77
	ds_read_b128 v[80:83], v100
	ds_read_b128 v[84:87], v100 offset:2048
	ds_read_b128 v[88:91], v79 offset:16384
	ds_read_b128 v[92:95], v79 offset:18432
	ds_read_b128 v[96:99], v100 offset:4096
	ds_read_b128 v[100:103], v100 offset:6144
	ds_read_b128 v[104:107], v79 offset:20480
	ds_read_b128 v[108:111], v79 offset:22528
	v_or_b32_e32 v79, s10, v78
	v_add_u32_e32 v132, v79, v75
	v_add_u32_e32 v79, v79, v77
	ds_read_b128 v[112:115], v132
	ds_read_b128 v[116:119], v132 offset:2048
	ds_read_b128 v[120:123], v79 offset:16384
	ds_read_b128 v[124:127], v79 offset:18432
	ds_read_b128 v[128:131], v132 offset:4096
	ds_read_b128 v[132:135], v132 offset:6144
	ds_read_b128 v[146:149], v79 offset:20480
	ds_read_b128 v[150:153], v79 offset:22528
	s_waitcnt lgkmcnt(0)
	v_mfma_f32_16x16x32_bf16 v[60:63], v[80:83], v[88:91], v[60:63]
	v_mfma_f32_16x16x32_bf16 v[56:59], v[80:83], v[92:95], v[56:59]
	v_mfma_f32_16x16x32_bf16 v[52:55], v[80:83], v[104:107], v[52:55]
	v_mfma_f32_16x16x32_bf16 v[48:51], v[80:83], v[108:111], v[48:51]
	v_mfma_f32_16x16x32_bf16 v[44:47], v[84:87], v[88:91], v[44:47]
	v_mfma_f32_16x16x32_bf16 v[40:43], v[84:87], v[92:95], v[40:43]
	v_mfma_f32_16x16x32_bf16 v[36:39], v[84:87], v[104:107], v[36:39]
	v_mfma_f32_16x16x32_bf16 v[32:35], v[84:87], v[108:111], v[32:35]
	v_mfma_f32_16x16x32_bf16 v[28:31], v[96:99], v[88:91], v[28:31]
	v_mfma_f32_16x16x32_bf16 v[24:27], v[96:99], v[92:95], v[24:27]
	v_mfma_f32_16x16x32_bf16 v[20:23], v[96:99], v[104:107], v[20:23]
	v_mfma_f32_16x16x32_bf16 v[16:19], v[96:99], v[108:111], v[16:19]
	v_mfma_f32_16x16x32_bf16 v[12:15], v[100:103], v[88:91], v[12:15]
	v_mfma_f32_16x16x32_bf16 v[8:11], v[100:103], v[92:95], v[8:11]
	v_mfma_f32_16x16x32_bf16 v[4:7], v[100:103], v[104:107], v[4:7]
	v_mfma_f32_16x16x32_bf16 v[0:3], v[100:103], v[108:111], v[0:3]
	v_mfma_f32_16x16x32_bf16 v[60:63], v[112:115], v[120:123], v[60:63]
	v_mfma_f32_16x16x32_bf16 v[56:59], v[112:115], v[124:127], v[56:59]
	v_mfma_f32_16x16x32_bf16 v[52:55], v[112:115], v[146:149], v[52:55]
	v_mfma_f32_16x16x32_bf16 v[48:51], v[112:115], v[150:153], v[48:51]
	v_mfma_f32_16x16x32_bf16 v[44:47], v[116:119], v[120:123], v[44:47]
	v_mfma_f32_16x16x32_bf16 v[40:43], v[116:119], v[124:127], v[40:43]
	v_mfma_f32_16x16x32_bf16 v[36:39], v[116:119], v[146:149], v[36:39]
	v_mfma_f32_16x16x32_bf16 v[32:35], v[116:119], v[150:153], v[32:35]
	v_mfma_f32_16x16x32_bf16 v[28:31], v[128:131], v[120:123], v[28:31]
	v_mfma_f32_16x16x32_bf16 v[24:27], v[128:131], v[124:127], v[24:27]
	v_mfma_f32_16x16x32_bf16 v[20:23], v[128:131], v[146:149], v[20:23]
	v_mfma_f32_16x16x32_bf16 v[16:19], v[128:131], v[150:153], v[16:19]
	v_mfma_f32_16x16x32_bf16 v[12:15], v[132:135], v[120:123], v[12:15]
	v_mfma_f32_16x16x32_bf16 v[8:11], v[132:135], v[124:127], v[8:11]
	v_mfma_f32_16x16x32_bf16 v[4:7], v[132:135], v[146:149], v[4:7]
	v_mfma_f32_16x16x32_bf16 v[0:3], v[132:135], v[150:153], v[0:3]
	s_add_i32 s9, s9, 0x8000
	s_waitcnt vmcnt(0)
	s_add_u32 s4, s4, 0x80
	s_addc_u32 s5, s5, 0
	s_cmpk_lg_i32 s4, 0x780
	s_barrier
	s_cbranch_scc1 .LBB0_1106
	s_setprio 0
	v_add_u32_e32 v74, v78, v77
	v_add_u32_e32 v102, v78, v75
	v_add_u32_e32 v122, v76, v77
	v_add_u32_e32 v130, v76, v75
	ds_read_b128 v[64:67], v74 offset:55296
	ds_read_b128 v[78:81], v74 offset:53248
	ds_read_b128 v[82:85], v102 offset:38912
	ds_read_b128 v[86:89], v102 offset:36864
	ds_read_b128 v[90:93], v74 offset:51200
	ds_read_b128 v[94:97], v74 offset:49152
	ds_read_b128 v[98:101], v102 offset:34816
	ds_read_b128 v[102:105], v102 offset:32768
	ds_read_b128 v[74:77], v122 offset:55296
	ds_read_b128 v[106:109], v122 offset:53248
	ds_read_b128 v[110:113], v130 offset:38912
	ds_read_b128 v[114:117], v130 offset:36864
	ds_read_b128 v[118:121], v122 offset:51200
	ds_read_b128 v[122:125], v122 offset:49152
	ds_read_b128 v[126:129], v130 offset:34816
	ds_read_b128 v[130:133], v130 offset:32768
	v_and_b32_e32 v134, 64, v69
	s_waitcnt lgkmcnt(0)
	v_mfma_f32_16x16x32_bf16 v[60:63], v[130:133], v[122:125], v[60:63]
	v_mfma_f32_16x16x32_bf16 v[56:59], v[130:133], v[118:121], v[56:59]
	v_mfma_f32_16x16x32_bf16 v[52:55], v[130:133], v[106:109], v[52:55]
	v_mfma_f32_16x16x32_bf16 v[48:51], v[130:133], v[74:77], v[48:51]
	v_mfma_f32_16x16x32_bf16 v[44:47], v[126:129], v[122:125], v[44:47]
	v_mfma_f32_16x16x32_bf16 v[40:43], v[126:129], v[118:121], v[40:43]
	v_mfma_f32_16x16x32_bf16 v[36:39], v[126:129], v[106:109], v[36:39]
	v_mfma_f32_16x16x32_bf16 v[32:35], v[126:129], v[74:77], v[32:35]
	v_mfma_f32_16x16x32_bf16 v[28:31], v[114:117], v[122:125], v[28:31]
	v_mfma_f32_16x16x32_bf16 v[24:27], v[114:117], v[118:121], v[24:27]
	v_mfma_f32_16x16x32_bf16 v[20:23], v[114:117], v[106:109], v[20:23]
	v_mfma_f32_16x16x32_bf16 v[16:19], v[114:117], v[74:77], v[16:19]
	v_mfma_f32_16x16x32_bf16 v[12:15], v[110:113], v[122:125], v[12:15]
	v_mfma_f32_16x16x32_bf16 v[8:11], v[110:113], v[118:121], v[8:11]
	v_mfma_f32_16x16x32_bf16 v[4:7], v[110:113], v[106:109], v[4:7]
	v_mfma_f32_16x16x32_bf16 v[0:3], v[110:113], v[74:77], v[0:3]
	v_mfma_f32_16x16x32_bf16 v[60:63], v[102:105], v[94:97], v[60:63]
	v_mfma_f32_16x16x32_bf16 v[56:59], v[102:105], v[90:93], v[56:59]
	v_mfma_f32_16x16x32_bf16 v[52:55], v[102:105], v[78:81], v[52:55]
	v_mfma_f32_16x16x32_bf16 v[48:51], v[102:105], v[64:67], v[48:51]
	v_mfma_f32_16x16x32_bf16 v[44:47], v[98:101], v[94:97], v[44:47]
	v_mfma_f32_16x16x32_bf16 v[40:43], v[98:101], v[90:93], v[40:43]
	v_mfma_f32_16x16x32_bf16 v[36:39], v[98:101], v[78:81], v[36:39]
	v_mfma_f32_16x16x32_bf16 v[32:35], v[98:101], v[64:67], v[32:35]
	v_mfma_f32_16x16x32_bf16 v[28:31], v[86:89], v[94:97], v[28:31]
	v_mfma_f32_16x16x32_bf16 v[24:27], v[86:89], v[90:93], v[24:27]
	v_mfma_f32_16x16x32_bf16 v[20:23], v[86:89], v[78:81], v[20:23]
	v_mfma_f32_16x16x32_bf16 v[16:19], v[86:89], v[64:67], v[16:19]
	v_mfma_f32_16x16x32_bf16 v[12:15], v[82:85], v[94:97], v[12:15]
	v_mfma_f32_16x16x32_bf16 v[8:11], v[82:85], v[90:93], v[8:11]
	v_mfma_f32_16x16x32_bf16 v[4:7], v[82:85], v[78:81], v[4:7]
	v_mfma_f32_16x16x32_bf16 v[0:3], v[82:85], v[64:67], v[0:3]
	s_movk_i32 s4, 0x2400
	v_mul_lo_u32 v64, v72, s4
	v_lshl_or_b32 v65, v73, 1, v64
	s_movk_i32 s4, 0x240
	v_cvt_pk_bf16_f32 v60, v60, s0
	v_mad_u32_u24 v65, v71, s4, v65
	v_cvt_pk_bf16_f32 v56, v56, s0
	v_cvt_pk_bf16_f32 v52, v52, s0
	v_cvt_pk_bf16_f32 v48, v48, s0
	v_cvt_pk_bf16_f32 v44, v44, s0
	v_cvt_pk_bf16_f32 v40, v40, s0
	v_cvt_pk_bf16_f32 v36, v36, s0
	v_cvt_pk_bf16_f32 v32, v32, s0
	v_cvt_pk_bf16_f32 v28, v28, s0
	v_cvt_pk_bf16_f32 v24, v24, s0
	v_cvt_pk_bf16_f32 v20, v20, s0
	v_cvt_pk_bf16_f32 v16, v16, s0
	v_cvt_pk_bf16_f32 v12, v12, s0
	v_cvt_pk_bf16_f32 v8, v8, s0
	v_cvt_pk_bf16_f32 v4, v4, s0
	v_cvt_pk_bf16_f32 v0, v0, s0
	s_waitcnt vmcnt(0)
	s_barrier
	ds_write_b16 v65, v60
	v_cvt_pk_bf16_f32 v60, v61, s0
	ds_write_b16 v65, v56 offset:32
	v_cvt_pk_bf16_f32 v56, v57, s0
	ds_write_b16 v65, v52 offset:64
	v_cvt_pk_bf16_f32 v52, v53, s0
	ds_write_b16 v65, v48 offset:96
	v_cvt_pk_bf16_f32 v48, v49, s0
	ds_write_b16 v65, v44 offset:2304
	v_cvt_pk_bf16_f32 v44, v45, s0
	ds_write_b16 v65, v40 offset:2336
	v_cvt_pk_bf16_f32 v40, v41, s0
	ds_write_b16 v65, v36 offset:2368
	v_cvt_pk_bf16_f32 v36, v37, s0
	ds_write_b16 v65, v32 offset:2400
	v_cvt_pk_bf16_f32 v32, v33, s0
	ds_write_b16 v65, v28 offset:4608
	v_cvt_pk_bf16_f32 v28, v29, s0
	ds_write_b16 v65, v24 offset:4640
	v_cvt_pk_bf16_f32 v24, v25, s0
	ds_write_b16 v65, v20 offset:4672
	v_cvt_pk_bf16_f32 v20, v21, s0
	ds_write_b16 v65, v16 offset:4704
	v_cvt_pk_bf16_f32 v16, v17, s0
	ds_write_b16 v65, v12 offset:6912
	v_cvt_pk_bf16_f32 v12, v13, s0
	ds_write_b16 v65, v8 offset:6944
	v_cvt_pk_bf16_f32 v8, v9, s0
	ds_write_b16 v65, v4 offset:6976
	v_cvt_pk_bf16_f32 v4, v5, s0
	ds_write_b16 v65, v0 offset:7008
	v_cvt_pk_bf16_f32 v0, v1, s0
	ds_write_b16 v65, v60 offset:144
	v_cvt_pk_bf16_f32 v60, v62, s0
	ds_write_b16 v65, v56 offset:176
	v_cvt_pk_bf16_f32 v56, v58, s0
	ds_write_b16 v65, v52 offset:208
	v_cvt_pk_bf16_f32 v52, v54, s0
	ds_write_b16 v65, v48 offset:240
	v_cvt_pk_bf16_f32 v48, v50, s0
	ds_write_b16 v65, v44 offset:2448
	v_cvt_pk_bf16_f32 v44, v46, s0
	ds_write_b16 v65, v40 offset:2480
	v_cvt_pk_bf16_f32 v40, v42, s0
	ds_write_b16 v65, v36 offset:2512
	v_cvt_pk_bf16_f32 v36, v38, s0
	ds_write_b16 v65, v32 offset:2544
	v_cvt_pk_bf16_f32 v32, v34, s0
	ds_write_b16 v65, v28 offset:4752
	v_cvt_pk_bf16_f32 v28, v30, s0
	ds_write_b16 v65, v24 offset:4784
	v_cvt_pk_bf16_f32 v24, v26, s0
	ds_write_b16 v65, v20 offset:4816
	v_cvt_pk_bf16_f32 v20, v22, s0
	ds_write_b16 v65, v16 offset:4848
	v_cvt_pk_bf16_f32 v16, v18, s0
	ds_write_b16 v65, v12 offset:7056
	v_cvt_pk_bf16_f32 v12, v14, s0
	ds_write_b16 v65, v8 offset:7088
	v_cvt_pk_bf16_f32 v8, v10, s0
	ds_write_b16 v65, v4 offset:7120
	v_cvt_pk_bf16_f32 v4, v6, s0
	ds_write_b16 v65, v0 offset:7152
	v_cvt_pk_bf16_f32 v0, v2, s0
	v_add_u32_e32 v5, s1, v70
	s_ashr_i32 s1, s0, 31
	ds_write_b16 v65, v60 offset:288
	v_cvt_pk_bf16_f32 v60, v63, s0
	ds_write_b16 v65, v56 offset:320
	v_cvt_pk_bf16_f32 v56, v59, s0
	ds_write_b16 v65, v52 offset:352
	v_cvt_pk_bf16_f32 v52, v55, s0
	ds_write_b16 v65, v48 offset:384
	v_cvt_pk_bf16_f32 v48, v51, s0
	ds_write_b16 v65, v44 offset:2592
	v_cvt_pk_bf16_f32 v44, v47, s0
	ds_write_b16 v65, v40 offset:2624
	v_cvt_pk_bf16_f32 v40, v43, s0
	ds_write_b16 v65, v36 offset:2656
	v_cvt_pk_bf16_f32 v36, v39, s0
	ds_write_b16 v65, v32 offset:2688
	v_cvt_pk_bf16_f32 v32, v35, s0
	ds_write_b16 v65, v28 offset:4896
	v_cvt_pk_bf16_f32 v28, v31, s0
	ds_write_b16 v65, v24 offset:4928
	v_cvt_pk_bf16_f32 v24, v27, s0
	ds_write_b16 v65, v20 offset:4960
	v_cvt_pk_bf16_f32 v20, v23, s0
	ds_write_b16 v65, v16 offset:4992
	v_cvt_pk_bf16_f32 v16, v19, s0
	ds_write_b16 v65, v12 offset:7200
	v_cvt_pk_bf16_f32 v12, v15, s0
	ds_write_b16 v65, v8 offset:7232
	v_cvt_pk_bf16_f32 v8, v11, s0
	ds_write_b16 v65, v4 offset:7264
	v_cvt_pk_bf16_f32 v4, v7, s0
	ds_write_b16 v65, v0 offset:7296
	v_cvt_pk_bf16_f32 v0, v3, s0
	s_lshl_b64 s[0:1], s[0:1], 1
	v_readlane_b32 s36, v246, 25
	ds_write_b16 v65, v0 offset:7440
	v_lshlrev_b32_e32 v0, 4, v69
	v_readlane_b32 s37, v246, 26
	s_add_u32 s0, s36, s0
	v_and_b32_e32 v0, 0x70, v0
	s_addc_u32 s1, s37, s1
	v_lshlrev_b32_e32 v136, 1, v134
	ds_write_b16 v65, v4 offset:7408
	v_or_b32_e32 v4, v64, v0
	v_lshl_add_u64 v[2:3], s[0:1], 0, v[136:137]
	s_movk_i32 s0, 0x90
	ds_write_b16 v65, v60 offset:432
	ds_write_b16 v65, v56 offset:464
	ds_write_b16 v65, v52 offset:496
	ds_write_b16 v65, v48 offset:528
	ds_write_b16 v65, v44 offset:2736
	ds_write_b16 v65, v40 offset:2768
	ds_write_b16 v65, v36 offset:2800
	ds_write_b16 v65, v32 offset:2832
	ds_write_b16 v65, v28 offset:5040
	ds_write_b16 v65, v24 offset:5072
	ds_write_b16 v65, v20 offset:5104
	ds_write_b16 v65, v16 offset:5136
	ds_write_b16 v65, v12 offset:7344
	ds_write_b16 v65, v8 offset:7376
	v_mov_b32_e32 v1, v137
	v_mad_u32_u24 v12, v68, s0, v4
	v_lshl_add_u64 v[8:9], v[2:3], 0, v[0:1]
	ds_read_b128 v[0:3], v12
	v_or_b32_e32 v13, v5, v68
	ds_read_b128 v[4:7], v12 offset:1152
	s_movk_i32 s4, 0x1a00
	v_mad_i64_i32 v[10:11], s[0:1], v13, s4, v[8:9]
	s_waitcnt lgkmcnt(1)
	global_store_dwordx4 v[10:11], v[0:3], off
	s_add_i32 s6, s6, 1
	s_movk_i32 s36, 0x880
	v_or_b32_e32 v0, 8, v13
	v_mad_i64_i32 v[0:1], s[0:1], v0, s4, v[8:9]
	s_waitcnt lgkmcnt(0)
	global_store_dwordx4 v[0:1], v[4:7], off
	ds_read_b128 v[0:3], v12 offset:2304
	v_readlane_b32 s38, v246, 27
	v_or_b32_e32 v4, 16, v13
	v_mad_i64_i32 v[10:11], s[0:1], v4, s4, v[8:9]
	ds_read_b128 v[4:7], v12 offset:3456
	s_waitcnt lgkmcnt(1)
	global_store_dwordx4 v[10:11], v[0:3], off
	v_readlane_b32 s39, v246, 28
	v_readlane_b32 s40, v246, 29
	v_or_b32_e32 v0, 24, v13
	v_mad_i64_i32 v[0:1], s[0:1], v0, s4, v[8:9]
	s_waitcnt lgkmcnt(0)
	global_store_dwordx4 v[0:1], v[4:7], off
	ds_read_b128 v[0:3], v12 offset:4608
	v_readlane_b32 s41, v246, 30
	v_or_b32_e32 v4, 32, v13
	v_mad_i64_i32 v[10:11], s[0:1], v4, s4, v[8:9]
	ds_read_b128 v[4:7], v12 offset:5760
	s_waitcnt lgkmcnt(1)
	global_store_dwordx4 v[10:11], v[0:3], off
	v_readlane_b32 s42, v246, 31
	v_readlane_b32 s43, v246, 32
	v_or_b32_e32 v0, 40, v13
	v_mad_i64_i32 v[0:1], s[0:1], v0, s4, v[8:9]
	s_waitcnt lgkmcnt(0)
	global_store_dwordx4 v[0:1], v[4:7], off
	ds_read_b128 v[0:3], v12 offset:6912
	v_readlane_b32 s44, v246, 33
	v_or_b32_e32 v4, 48, v13
	v_mad_i64_i32 v[10:11], s[0:1], v4, s4, v[8:9]
	ds_read_b128 v[4:7], v12 offset:8064
	s_waitcnt lgkmcnt(1)
	global_store_dwordx4 v[10:11], v[0:3], off
	v_readlane_b32 s45, v246, 34
	v_readlane_b32 s46, v246, 35
	v_or_b32_e32 v0, 56, v13
	v_mad_i64_i32 v[0:1], s[0:1], v0, s4, v[8:9]
	s_mov_b64 s[0:1], 0
	v_readlane_b32 s47, v246, 36
	v_readlane_b32 s48, v246, 37
	v_readlane_b32 s49, v246, 38
	v_readlane_b32 s50, v246, 39
	v_readlane_b32 s51, v246, 40
	s_waitcnt lgkmcnt(0)
	global_store_dwordx4 v[0:1], v[4:7], off
	s_barrier
	s_branch .LBB0_1095
